# baseline (speedup 1.0000x reference)
; #define MFMA(a, b, c) __builtin_amdgcn_mfma_f32_16x16x32_bf16((a), (b), (c), 0, 0, 0)
; __device__ __forceinline__ void phase_dif_attn(const Params& p, char* lds) {
;     ...
;     gload(0); lwrite(0);
;     __syncthreads();
;     for (int kt = 0; kt < ntile; ++kt) {
;       const char* kb = lds + (kt & 1) * BUFB; const char* vbuf = kb + KB;
;       if (kt + 1 < ntile) gload(kt + 1);
;       f32x4 st[2][4];
; #pragma unroll
;       for (int mi = 0; mi < 2; ++mi)
; #pragma unroll
;         for (int n = 0; n < 4; ++n) st[mi][n] = f32x4{0.f, 0.f, 0.f, 0.f};
; #pragma unroll
;       for (int kk = 0; kk < 2; ++kk)
; #pragma unroll
;         for (int n = 0; n < 4; ++n) {
;           bf16x8 ka = *(const bf16x8*)(kb + kk * 4096 + (n * 16 + l15) * 64 + quad * 16);
; #pragma unroll
;           for (int mi = 0; mi < 2; ++mi) st[mi][n] = MFMA(ka, qf[mi][kk], st[mi][n]);
;         }
;       bf16x8 pb[2][2];
; #pragma unroll
;       for (int mi = 0; mi < 2; ++mi) {
;         float mx = -1e30f;
; #pragma unroll
;         for (int n = 0; n < 4; ++n)
; #pragma unroll
;           for (int j = 0; j < 4; ++j) mx = fmaxf(mx, st[mi][n][j]);
;         mx = fmaxf(mx, __shfl_xor(mx, 16)); mx = fmaxf(mx, __shfl_xor(mx, 32));
;         float mnew = mrun[mi], alpha = 1.f;
;         if (!__all(mx - mrun[mi] <= 8.f)) {
;           mnew = fmaxf(mrun[mi], mx);
;           alpha = __builtin_amdgcn_exp2f(mrun[mi] - mnew);
;           mrun[mi] = mnew;
; #pragma unroll
;           for (int dv = 0; dv < 8; ++dv) oacc[mi][dv] *= alpha;
;         }
.LBB0_500:
	s_and_b32 s0, s1, 15
	v_add_u32_e32 v144, s6, v131
	s_lshl_b32 s86, s0, 7
	v_ashrrev_i32_e32 v145, 31, v144
	v_lshl_add_u64 v[0:1], v[132:133], 0, s[86:87]
	v_lshlrev_b64 v[2:3], 11, v[144:145]
	v_add_u32_e32 v142, 16, v144
	v_lshl_add_u64 v[2:3], v[0:1], 0, v[2:3]
	v_ashrrev_i32_e32 v143, 31, v142
	global_load_dwordx4 v[72:75], v[2:3], off
	global_load_dwordx4 v[64:67], v[2:3], off offset:64
	v_lshlrev_b64 v[2:3], 11, v[142:143]
	v_lshl_add_u64 v[0:1], v[0:1], 0, v[2:3]
	global_load_dwordx4 v[76:79], v[0:1], off
	global_load_dwordx4 v[68:71], v[0:1], off offset:64
	v_add_u32_e32 v0, s4, v127
	v_ashrrev_i32_e32 v1, 31, v0
	v_readlane_b32 s6, v254, 26
	v_lshlrev_b64 v[0:1], 11, v[0:1]
	v_readlane_b32 s7, v254, 27
	s_lshl_b32 s1, s1, 13
	s_and_b32 s1, s1, 0x1c000
	v_lshl_add_u64 v[0:1], s[6:7], 0, v[0:1]
	s_ashr_i32 s6, s4, 6
	s_ashr_i32 s7, s6, 31
	s_lshl_b64 s[6:7], s[6:7], 17
	v_readlane_b32 s8, v254, 28
	v_readlane_b32 s9, v254, 29
	s_add_u32 s4, s8, s6
	s_addc_u32 s7, s9, s7
	v_lshl_add_u64 v[0:1], v[0:1], 0, s[86:87]
	s_add_u32 s6, s4, s1
	v_lshl_add_u64 v[0:1], v[0:1], 0, v[128:129]
	s_addc_u32 s7, s7, 0
	global_load_dwordx4 v[0:3], v[0:1], off
	v_lshl_add_u64 v[4:5], s[6:7], 0, v[134:135]
	global_load_dwordx4 v[4:7], v[4:5], off
	v_lshl_add_u64 v[8:9], s[6:7], 0, v[136:137]
	global_load_dwordx4 v[8:11], v[8:9], off
	s_add_u32 s1, s8, s1
	v_lshl_add_u64 v[146:147], v[138:139], 0, s[86:87]
	s_addc_u32 s4, s9, 0
	s_add_i32 s5, s5, 1
	s_mov_b32 s6, 0
	v_mov_b32_e32 v164, 0
	v_mov_b32_e32 v162, 0xf149f2ca
	s_mov_b32 s7, 64
	v_mov_b32_e32 v163, 0xf149f2ca
	v_mov_b32_e32 v165, 0
	s_waitcnt vmcnt(2)
	ds_write_b128 v159, v[0:3]
	s_waitcnt vmcnt(1)
	ds_write_b128 v160, v[4:7] offset:8192
	s_waitcnt vmcnt(0)
	ds_write_b128 v161, v[8:11] offset:8192
	v_mov_b32_e32 v2, v129
	v_mov_b32_e32 v3, v129
	v_mov_b32_e32 v0, v129
	v_mov_b32_e32 v1, v129
	v_mov_b64_e32 v[10:11], v[2:3]
	v_mov_b64_e32 v[18:19], v[2:3]
	v_mov_b64_e32 v[26:27], v[2:3]
	v_mov_b64_e32 v[34:35], v[2:3]
	v_mov_b64_e32 v[42:43], v[2:3]
	v_mov_b64_e32 v[54:55], v[2:3]
	v_mov_b64_e32 v[58:59], v[2:3]
	v_mov_b64_e32 v[6:7], v[2:3]
	v_mov_b64_e32 v[14:15], v[2:3]
	v_mov_b64_e32 v[22:23], v[2:3]
	v_mov_b64_e32 v[30:31], v[2:3]
	v_mov_b64_e32 v[38:39], v[2:3]
	v_mov_b64_e32 v[46:47], v[2:3]
	v_mov_b64_e32 v[50:51], v[2:3]
	v_mov_b64_e32 v[62:63], v[2:3]
	v_mov_b64_e32 v[8:9], v[0:1]
	v_mov_b64_e32 v[16:17], v[0:1]
	v_mov_b64_e32 v[24:25], v[0:1]
	v_mov_b64_e32 v[32:33], v[0:1]
	v_mov_b64_e32 v[40:41], v[0:1]
	v_mov_b64_e32 v[52:53], v[0:1]
	v_mov_b64_e32 v[56:57], v[0:1]
	v_mov_b64_e32 v[4:5], v[0:1]
	v_mov_b64_e32 v[12:13], v[0:1]
	v_mov_b64_e32 v[20:21], v[0:1]
	v_mov_b64_e32 v[28:29], v[0:1]
	v_mov_b64_e32 v[36:37], v[0:1]
	v_mov_b64_e32 v[44:45], v[0:1]
	v_mov_b64_e32 v[48:49], v[0:1]
	v_mov_b64_e32 v[60:61], v[0:1]
	v_mov_b32_e32 v240, 0
	v_mov_b32_e32 v241, 0
	v_mov_b32_e32 v242, 0
	v_mov_b32_e32 v243, 0
	v_mov_b32_e32 v244, 0
	v_mov_b32_e32 v245, 0
	v_mov_b32_e32 v246, 0
	v_mov_b32_e32 v247, 0
	s_mov_b32 s100, 0xf149f2ca
	s_mov_b32 s101, 0xf149f2ca
	s_mov_b32 s8, 0
	v_add3_u32 v148, s8, v126, v156
	v_add3_u32 v198, s8, v125, v124
	s_waitcnt lgkmcnt(0)
	s_barrier
.LBB0_501:
	ds_read_b128 v[178:181], v148
	ds_read_b128 v[182:185], v148 offset:1024
	ds_read_b128 v[186:189], v148 offset:2048
	ds_read_b128 v[190:193], v148 offset:3072
	ds_read_b128 v[194:197], v148 offset:4096
	ds_read_b128 v[228:231], v148 offset:5120
	ds_read_b128 v[232:235], v148 offset:6144
	ds_read_b128 v[236:239], v148 offset:7168
	s_cmp_lt_u32 s6, 3
	s_cselect_b32 s9, 8, 13
	s_cselect_b32 s62, s77, 0xffffff00
	s_lshl_b32 s9, s3, s9
	s_add_i32 s62, s62, s9
	s_add_i32 s9, s7, s62
	s_ashr_i32 s62, s9, 6
	s_ashr_i32 s63, s62, 31
	v_add_u32_e32 v80, s9, v127
	s_lshl_b64 s[62:63], s[62:63], 17
	v_ashrrev_i32_e32 v81, 31, v80
	s_add_u32 s62, s1, s62
	v_lshlrev_b64 v[80:81], 11, v[80:81]
	s_addc_u32 s63, s4, s63
	v_lshl_add_u64 v[80:81], v[146:147], 0, v[80:81]
	v_lshl_add_u64 v[84:85], s[62:63], 0, v[134:135]
	v_lshl_add_u64 v[88:89], s[62:63], 0, v[136:137]
	global_load_dwordx4 v[80:83], v[80:81], off
	global_load_dwordx4 v[84:87], v[84:85], off
	global_load_dwordx4 v[88:91], v[88:89], off
	s_waitcnt lgkmcnt(7)
	v_mfma_f32_16x16x32_bf16 v[120:123], v[178:181], v[72:75], v[240:243]
	v_mfma_f32_16x16x32_bf16 v[104:107], v[178:181], v[76:79], v[244:247]
	s_waitcnt lgkmcnt(6)
	v_mfma_f32_16x16x32_bf16 v[116:119], v[182:185], v[72:75], v[240:243]
	v_mfma_f32_16x16x32_bf16 v[100:103], v[182:185], v[76:79], v[244:247]
	s_waitcnt lgkmcnt(5)
	v_mfma_f32_16x16x32_bf16 v[112:115], v[186:189], v[72:75], v[240:243]
	v_mfma_f32_16x16x32_bf16 v[96:99], v[186:189], v[76:79], v[244:247]
	s_waitcnt lgkmcnt(4)
	v_mfma_f32_16x16x32_bf16 v[108:111], v[190:193], v[72:75], v[240:243]
	v_mfma_f32_16x16x32_bf16 v[92:95], v[190:193], v[76:79], v[244:247]
	s_waitcnt lgkmcnt(3)
	v_mfma_f32_16x16x32_bf16 v[120:123], v[194:197], v[64:67], v[120:123]
	v_mfma_f32_16x16x32_bf16 v[104:107], v[194:197], v[68:71], v[104:107]
	s_waitcnt lgkmcnt(2)
	v_mfma_f32_16x16x32_bf16 v[116:119], v[228:231], v[64:67], v[116:119]
	v_mfma_f32_16x16x32_bf16 v[100:103], v[228:231], v[68:71], v[100:103]
	s_waitcnt lgkmcnt(1)
	v_mfma_f32_16x16x32_bf16 v[112:115], v[232:235], v[64:67], v[112:115]
	v_mfma_f32_16x16x32_bf16 v[96:99], v[232:235], v[68:71], v[96:99]
	s_waitcnt lgkmcnt(0)
	v_mfma_f32_16x16x32_bf16 v[108:111], v[236:239], v[64:67], v[108:111]
	v_mfma_f32_16x16x32_bf16 v[92:95], v[236:239], v[68:71], v[92:95]
	ds_read_b64 v[178:179], v198 offset:8192
	ds_read_b64 v[180:181], v198 offset:8224
	ds_read_b64 v[182:183], v198 offset:10496
	ds_read_b64 v[184:185], v198 offset:10528
	ds_read_b64 v[186:187], v198 offset:12800
	ds_read_b64 v[188:189], v198 offset:12832
	ds_read_b64 v[190:191], v198 offset:15104
	ds_read_b64 v[192:193], v198 offset:15136
	ds_read_b64 v[194:195], v198 offset:17408
	ds_read_b64 v[196:197], v198 offset:17440
	ds_read_b64 v[228:229], v198 offset:19712
	ds_read_b64 v[230:231], v198 offset:19744
	ds_read_b64 v[232:233], v198 offset:22016
	ds_read_b64 v[234:235], v198 offset:22048
	v_max3_f32 v148, v120, s21, v121
	v_max3_f32 v148, v148, v122, v123
	v_max3_f32 v148, v148, v116, v117
	v_max3_f32 v148, v148, v118, v119
	v_max3_f32 v148, v148, v112, v113
	v_max3_f32 v148, v148, v114, v115
	v_max3_f32 v148, v148, v108, v109
	v_max3_f32 v148, v148, v110, v111
	v_max3_f32 v150, v104, s21, v105
	v_max3_f32 v150, v150, v106, v107
	v_max3_f32 v150, v150, v100, v101
	v_max3_f32 v150, v150, v102, v103
	v_max3_f32 v150, v150, v96, v97
	v_max3_f32 v150, v150, v98, v99
	v_max3_f32 v150, v150, v92, v93
	v_max3_f32 v150, v150, v94, v95
	v_cmp_ge_f32_e32 vcc, s100, v148
	s_nop 0
	s_cmp_eq_u64 vcc, exec
	s_cbranch_scc0 .Lattn_slow0

; __device__ __forceinline__ unsigned cvtpk(float lo, float hi) { f32x2_t v = {lo, hi}; bf16x2_t r = __builtin_convertvector(v, bf16x2_t); return *reinterpret_cast<unsigned*>(&r); }
; #define MFMA(a, b, c) __builtin_amdgcn_mfma_f32_16x16x32_bf16((a), (b), (c), 0, 0, 0)
; __device__ __forceinline__ void phase_dif_attn(const Params& p, char* lds) {
;     ...
;         float rsum = 0.f;
; #pragma unroll
;         for (int n = 0; n < 4; ++n)
; #pragma unroll
;           for (int j = 0; j < 4; ++j) { float pv = __builtin_amdgcn_exp2f(st[mi][n][j] - mnew); st[mi][n][j] = pv; rsum += pv; }
;         lrun[mi] = lrun[mi] * alpha + rsum;
; #pragma unroll
;         for (int ks = 0; ks < 2; ++ks) {
;           u32x4 v = {cvtpk(st[mi][2 * ks][0], st[mi][2 * ks][1]), cvtpk(st[mi][2 * ks][2], st[mi][2 * ks][3]),
;                      cvtpk(st[mi][2 * ks + 1][0], st[mi][2 * ks + 1][1]), cvtpk(st[mi][2 * ks + 1][2], st[mi][2 * ks + 1][3])};
;           pb[mi][ks] = *reinterpret_cast<bf16x8*>(&v);
;         }
;       }
; #pragma unroll
;       for (int dv = 0; dv < 8; ++dv)
; #pragma unroll
;         for (int ks = 0; ks < 2; ++ks) {
;           const char* vp = vbuf + (dv * 16 + l15) * 144 + (ks * 32 + quad * 4) * 2;
;           bf16x4 lo = *(const bf16x4*)vp, hi = *(const bf16x4*)(vp + 32);
;           bf16x8 va = {lo[0], lo[1], lo[2], lo[3], hi[0], hi[1], hi[2], hi[3]};
; #pragma unroll
;           for (int mi = 0; mi < 2; ++mi) oacc[mi][dv] = MFMA(va, pb[mi][ks], oacc[mi][dv]);
;           if (ks == 1 && (dv & 1)) __builtin_amdgcn_sched_barrier(0);
;         }
;       if (kt + 1 < ntile) lwrite((kt + 1) & 1);
;       __syncthreads();
.Lattn_back1:
	v_exp_f32_e32 v120, v120
	v_exp_f32_e32 v104, v104
	v_exp_f32_e32 v121, v121
	v_exp_f32_e32 v105, v105
	v_exp_f32_e32 v122, v122
	v_exp_f32_e32 v106, v106
	v_exp_f32_e32 v123, v123
	v_exp_f32_e32 v107, v107
	v_exp_f32_e32 v116, v116
	v_exp_f32_e32 v100, v100
	v_exp_f32_e32 v117, v117
	v_exp_f32_e32 v101, v101
	v_exp_f32_e32 v118, v118
	v_exp_f32_e32 v102, v102
	v_exp_f32_e32 v119, v119
	v_exp_f32_e32 v103, v103
	v_add_f32_e32 v165, v165, v120
	v_add_f32_e32 v164, v164, v104
	v_add_f32_e32 v165, v165, v121
	v_add_f32_e32 v164, v164, v105
	v_add_f32_e32 v165, v165, v122
	v_add_f32_e32 v164, v164, v106
	v_add_f32_e32 v165, v165, v123
	v_add_f32_e32 v164, v164, v107
	v_add_f32_e32 v165, v165, v116
	v_add_f32_e32 v164, v164, v100
	v_add_f32_e32 v165, v165, v117
	v_add_f32_e32 v164, v164, v101
	v_add_f32_e32 v165, v165, v118
	v_add_f32_e32 v164, v164, v102
	v_add_f32_e32 v165, v165, v119
	v_add_f32_e32 v164, v164, v103
	v_cvt_pk_bf16_f32 v166, v120, v121
	v_cvt_pk_bf16_f32 v167, v122, v123
	v_cvt_pk_bf16_f32 v168, v116, v117
	v_cvt_pk_bf16_f32 v169, v118, v119
	v_cvt_pk_bf16_f32 v170, v104, v105
	v_cvt_pk_bf16_f32 v171, v106, v107
	v_cvt_pk_bf16_f32 v172, v100, v101
	v_cvt_pk_bf16_f32 v173, v102, v103
	v_exp_f32_e32 v112, v112
	v_exp_f32_e32 v96, v96
	s_waitcnt lgkmcnt(12)
	v_mfma_f32_16x16x32_bf16 v[60:63], v[178:181], v[166:169], v[60:63]
	v_exp_f32_e32 v113, v113
	v_exp_f32_e32 v97, v97
	v_exp_f32_e32 v114, v114
	v_mfma_f32_16x16x32_bf16 v[56:59], v[178:181], v[170:173], v[56:59]
	v_exp_f32_e32 v98, v98
	v_exp_f32_e32 v115, v115
	ds_read_b64 v[236:237], v198 offset:24320
	ds_read_b64 v[238:239], v198 offset:24352
	s_waitcnt lgkmcnt(12)
	v_mfma_f32_16x16x32_bf16 v[48:51], v[182:185], v[166:169], v[48:51]
	v_exp_f32_e32 v99, v99
	v_exp_f32_e32 v108, v108
	v_exp_f32_e32 v92, v92
	v_mfma_f32_16x16x32_bf16 v[52:55], v[182:185], v[170:173], v[52:55]
	v_exp_f32_e32 v109, v109
	v_exp_f32_e32 v93, v93
	ds_read_b64 v[178:179], v198 offset:8256
	ds_read_b64 v[180:181], v198 offset:8288
	s_waitcnt lgkmcnt(12)
	v_mfma_f32_16x16x32_bf16 v[44:47], v[186:189], v[166:169], v[44:47]
	v_exp_f32_e32 v110, v110
	v_exp_f32_e32 v94, v94
	v_exp_f32_e32 v111, v111
	v_mfma_f32_16x16x32_bf16 v[40:43], v[186:189], v[170:173], v[40:43]
	v_exp_f32_e32 v95, v95
	v_add_f32_e32 v165, v165, v112
	ds_read_b64 v[182:183], v198 offset:10560
	ds_read_b64 v[184:185], v198 offset:10592
	s_waitcnt lgkmcnt(12)
	v_mfma_f32_16x16x32_bf16 v[36:39], v[190:193], v[166:169], v[36:39]
	v_add_f32_e32 v164, v164, v96
	v_add_f32_e32 v165, v165, v113
	v_add_f32_e32 v164, v164, v97
	v_mfma_f32_16x16x32_bf16 v[32:35], v[190:193], v[170:173], v[32:35]
	v_add_f32_e32 v165, v165, v114
	v_add_f32_e32 v164, v164, v98
	ds_read_b64 v[186:187], v198 offset:12864
	ds_read_b64 v[188:189], v198 offset:12896
	s_waitcnt lgkmcnt(12)
	v_mfma_f32_16x16x32_bf16 v[28:31], v[194:197], v[166:169], v[28:31]
	v_add_f32_e32 v165, v165, v115
	v_add_f32_e32 v164, v164, v99
	v_add_f32_e32 v165, v165, v108
	v_mfma_f32_16x16x32_bf16 v[24:27], v[194:197], v[170:173], v[24:27]
	v_add_f32_e32 v164, v164, v92
	v_add_f32_e32 v165, v165, v109
	ds_read_b64 v[190:191], v198 offset:15168
	ds_read_b64 v[192:193], v198 offset:15200
	s_waitcnt lgkmcnt(12)
	v_mfma_f32_16x16x32_bf16 v[20:23], v[228:231], v[166:169], v[20:23]
	v_add_f32_e32 v164, v164, v93
	v_add_f32_e32 v165, v165, v110
	v_add_f32_e32 v164, v164, v94
	v_mfma_f32_16x16x32_bf16 v[16:19], v[228:231], v[170:173], v[16:19]
	v_add_f32_e32 v165, v165, v111
	v_add_f32_e32 v164, v164, v95
	ds_read_b64 v[194:195], v198 offset:17472
	ds_read_b64 v[196:197], v198 offset:17504
	s_waitcnt lgkmcnt(12)
	v_mfma_f32_16x16x32_bf16 v[12:15], v[232:235], v[166:169], v[12:15]
	v_cvt_pk_bf16_f32 v174, v112, v113
	v_cvt_pk_bf16_f32 v175, v114, v115
	v_cvt_pk_bf16_f32 v176, v108, v109
	v_mfma_f32_16x16x32_bf16 v[8:11], v[232:235], v[170:173], v[8:11]
	v_cvt_pk_bf16_f32 v177, v110, v111
	v_cvt_pk_bf16_f32 v248, v96, v97
	ds_read_b64 v[228:229], v198 offset:19776
	ds_read_b64 v[230:231], v198 offset:19808
	s_waitcnt lgkmcnt(12)
	v_mfma_f32_16x16x32_bf16 v[4:7], v[236:239], v[166:169], v[4:7]
	v_cvt_pk_bf16_f32 v249, v98, v99
	v_cvt_pk_bf16_f32 v250, v92, v93
	v_cvt_pk_bf16_f32 v251, v94, v95
	v_mfma_f32_16x16x32_bf16 v[0:3], v[236:239], v[170:173], v[0:3]
	ds_read_b64 v[232:233], v198 offset:22080
	ds_read_b64 v[234:235], v198 offset:22112
	s_add_i32 s6, s6, 1
	s_waitcnt lgkmcnt(12)
	v_mfma_f32_16x16x32_bf16 v[60:63], v[178:181], v[174:177], v[60:63]
	v_mfma_f32_16x16x32_bf16 v[56:59], v[178:181], v[248:251], v[56:59]
	ds_read_b64 v[236:237], v198 offset:24384
	ds_read_b64 v[238:239], v198 offset:24416
	s_waitcnt lgkmcnt(12)
	v_mfma_f32_16x16x32_bf16 v[48:51], v[182:185], v[174:177], v[48:51]
	v_mfma_f32_16x16x32_bf16 v[52:55], v[182:185], v[248:251], v[52:55]
	s_waitcnt lgkmcnt(10)
	v_mfma_f32_16x16x32_bf16 v[44:47], v[186:189], v[174:177], v[44:47]
	v_mfma_f32_16x16x32_bf16 v[40:43], v[186:189], v[248:251], v[40:43]
	s_bitcmp1_b32 s6, 0
	s_cselect_b32 s8, 0x6800, 0
	s_add_i32 s8, s8, 0
	v_add_u32_e32 v92, s8, v149
	v_add3_u32 v92, v92, v151, v152
	s_waitcnt vmcnt(2)
	ds_write_b128 v92, v[80:83]
	v_add3_u32 v80, s8, v153, v154
	s_add_i32 s7, s7, 64
	s_waitcnt vmcnt(1)
	ds_write_b128 v80, v[84:87] offset:8192
	v_add3_u32 v80, s8, v155, v154
	s_waitcnt vmcnt(0)
	ds_write_b128 v80, v[88:91] offset:8192
	s_waitcnt lgkmcnt(11)
	v_mfma_f32_16x16x32_bf16 v[36:39], v[190:193], v[174:177], v[36:39]
	v_mfma_f32_16x16x32_bf16 v[32:35], v[190:193], v[248:251], v[32:35]
	s_waitcnt lgkmcnt(9)
	v_mfma_f32_16x16x32_bf16 v[28:31], v[194:197], v[174:177], v[28:31]
	v_mfma_f32_16x16x32_bf16 v[24:27], v[194:197], v[248:251], v[24:27]
	s_waitcnt lgkmcnt(7)
	v_mfma_f32_16x16x32_bf16 v[20:23], v[228:231], v[174:177], v[20:23]
	v_mfma_f32_16x16x32_bf16 v[16:19], v[228:231], v[248:251], v[16:19]
	s_waitcnt lgkmcnt(5)
	v_mfma_f32_16x16x32_bf16 v[12:15], v[232:235], v[174:177], v[12:15]
	v_mfma_f32_16x16x32_bf16 v[8:11], v[232:235], v[248:251], v[8:11]
	s_waitcnt lgkmcnt(3)
	v_mfma_f32_16x16x32_bf16 v[4:7], v[236:239], v[174:177], v[4:7]
	v_mfma_f32_16x16x32_bf16 v[0:3], v[236:239], v[248:251], v[0:3]
	v_mov_b32_e32 v116, v165
	v_mov_b32_e32 v101, v164
	v_add3_u32 v148, s8, v126, v156
	v_add3_u32 v198, s8, v125, v124
	s_cmp_eq_u32 s5, s6
	s_waitcnt lgkmcnt(0)
	s_barrier
	s_cbranch_scc0 .LBB0_501
	s_branch .LBB0_508
